# barrier leaders no longer bump the per-XCD generation word (nothing waits on it): one atomic less before the leader workgroup resumes
# speedup vs baseline: 1.0024x; 1.0024x over previous
; __device__ __forceinline__ unsigned xb_ld(unsigned* p)              { return __hip_atomic_load(p, __ATOMIC_RELAXED, __HIP_MEMORY_SCOPE_AGENT); }
; __device__ __forceinline__ unsigned xb_add(unsigned* p, unsigned v) { return __hip_atomic_fetch_add(p, v, __ATOMIC_RELAXED, __HIP_MEMORY_SCOPE_AGENT); }
; #define XB_SPIN(cond, bar) do { unsigned _sp = 0; while (cond) { __builtin_amdgcn_s_sleep(1); \
;     if ((++_sp & 255u) == 0u) { if (xb_ld(&(bar)[XB_TMO])) break; if (_sp > XB_SPIN_CAP) { atomicAdd(&(bar)[XB_TMO], 1u); break; } } } } while (0)
; __device__ __forceinline__ void xcd_barrier(const XcdBarrier& b) {
;     ...
;             __builtin_amdgcn_fence(__ATOMIC_RELEASE, "agent");
;             asm volatile("s_waitcnt vmcnt(0)" ::: "memory");
;             const unsigned og = xb_add(&bar[XB_TOP], 1u);
;             const unsigned tg = og / nx;
;             if (og + 1u == (tg + 1u) * nx) xb_add(&bar[XB_TOPGEN], 1u);
;             else XB_SPIN(xb_ld(&bar[XB_TOPGEN]) == tg, bar);
;             __builtin_amdgcn_fence(__ATOMIC_ACQUIRE, "agent");
;             xb_add(&bar[XB_XGEN(b.x)], 1u);
;             asm volatile("s_waitcnt vmcnt(0)" ::: "memory");
.LBB0_244:
	s_or_b64 exec, exec, s[4:5]
	v_mov_b32_e32 v0, s27
	v_add_co_u32_e32 v0, vcc, 0x2000, v0
	v_mov_b32_e32 v1, s26
	s_nop 0
	v_addc_co_u32_e32 v1, vcc, 0, v1, vcc
	v_mov_b32_e32 v2, 1
	s_waitcnt vmcnt(0) lgkmcnt(0)
	buffer_inv sc1
	s_waitcnt vmcnt(0)

; __device__ __forceinline__ unsigned xb_ld(unsigned* p)              { return __hip_atomic_load(p, __ATOMIC_RELAXED, __HIP_MEMORY_SCOPE_AGENT); }
; __device__ __forceinline__ unsigned xb_add(unsigned* p, unsigned v) { return __hip_atomic_fetch_add(p, v, __ATOMIC_RELAXED, __HIP_MEMORY_SCOPE_AGENT); }
; #define XB_SPIN(cond, bar) do { unsigned _sp = 0; while (cond) { __builtin_amdgcn_s_sleep(1); \
;     if ((++_sp & 255u) == 0u) { if (xb_ld(&(bar)[XB_TMO])) break; if (_sp > XB_SPIN_CAP) { atomicAdd(&(bar)[XB_TMO], 1u); break; } } } } while (0)
; __device__ __forceinline__ void xcd_barrier(const XcdBarrier& b) {
;     ...
;             __builtin_amdgcn_fence(__ATOMIC_RELEASE, "agent");
;             asm volatile("s_waitcnt vmcnt(0)" ::: "memory");
;             const unsigned og = xb_add(&bar[XB_TOP], 1u);
;             const unsigned tg = og / nx;
;             if (og + 1u == (tg + 1u) * nx) xb_add(&bar[XB_TOPGEN], 1u);
;             else XB_SPIN(xb_ld(&bar[XB_TOPGEN]) == tg, bar);
;             __builtin_amdgcn_fence(__ATOMIC_ACQUIRE, "agent");
;             xb_add(&bar[XB_XGEN(b.x)], 1u);
;             asm volatile("s_waitcnt vmcnt(0)" ::: "memory");
.LBB0_594:
	s_or_b64 exec, exec, s[0:1]
	v_mov_b32_e32 v0, s27
	v_add_co_u32_e32 v0, vcc, 0x2000, v0
	v_mov_b32_e32 v1, s26
	s_nop 0
	v_addc_co_u32_e32 v1, vcc, 0, v1, vcc
	v_mov_b32_e32 v2, 1
	s_waitcnt vmcnt(0) lgkmcnt(0)
	buffer_inv sc1
	s_waitcnt vmcnt(0)

; __device__ __forceinline__ unsigned xb_ld(unsigned* p)              { return __hip_atomic_load(p, __ATOMIC_RELAXED, __HIP_MEMORY_SCOPE_AGENT); }
; __device__ __forceinline__ unsigned xb_add(unsigned* p, unsigned v) { return __hip_atomic_fetch_add(p, v, __ATOMIC_RELAXED, __HIP_MEMORY_SCOPE_AGENT); }
; #define XB_SPIN(cond, bar) do { unsigned _sp = 0; while (cond) { __builtin_amdgcn_s_sleep(1); \
;     if ((++_sp & 255u) == 0u) { if (xb_ld(&(bar)[XB_TMO])) break; if (_sp > XB_SPIN_CAP) { atomicAdd(&(bar)[XB_TMO], 1u); break; } } } } while (0)
; __device__ __forceinline__ void xcd_barrier(const XcdBarrier& b) {
;     ...
;             __builtin_amdgcn_fence(__ATOMIC_RELEASE, "agent");
;             asm volatile("s_waitcnt vmcnt(0)" ::: "memory");
;             const unsigned og = xb_add(&bar[XB_TOP], 1u);
;             const unsigned tg = og / nx;
;             if (og + 1u == (tg + 1u) * nx) xb_add(&bar[XB_TOPGEN], 1u);
;             else XB_SPIN(xb_ld(&bar[XB_TOPGEN]) == tg, bar);
;             __builtin_amdgcn_fence(__ATOMIC_ACQUIRE, "agent");
;             xb_add(&bar[XB_XGEN(b.x)], 1u);
;             asm volatile("s_waitcnt vmcnt(0)" ::: "memory");
.LBB0_814:
	s_or_b64 exec, exec, s[0:1]
	v_mov_b32_e32 v0, s29
	v_add_co_u32_e32 v0, vcc, 0x2000, v0
	v_mov_b32_e32 v1, s28
	s_nop 0
	v_addc_co_u32_e32 v1, vcc, 0, v1, vcc
	v_mov_b32_e32 v2, 1
	s_waitcnt vmcnt(0) lgkmcnt(0)
	buffer_inv sc1
	s_waitcnt vmcnt(0)

; __device__ __forceinline__ unsigned xb_ld(unsigned* p)              { return __hip_atomic_load(p, __ATOMIC_RELAXED, __HIP_MEMORY_SCOPE_AGENT); }
; __device__ __forceinline__ unsigned xb_add(unsigned* p, unsigned v) { return __hip_atomic_fetch_add(p, v, __ATOMIC_RELAXED, __HIP_MEMORY_SCOPE_AGENT); }
; #define XB_SPIN(cond, bar) do { unsigned _sp = 0; while (cond) { __builtin_amdgcn_s_sleep(1); \
;     if ((++_sp & 255u) == 0u) { if (xb_ld(&(bar)[XB_TMO])) break; if (_sp > XB_SPIN_CAP) { atomicAdd(&(bar)[XB_TMO], 1u); break; } } } } while (0)
; __device__ __forceinline__ void xcd_barrier(const XcdBarrier& b) {
;     ...
;             __builtin_amdgcn_fence(__ATOMIC_RELEASE, "agent");
;             asm volatile("s_waitcnt vmcnt(0)" ::: "memory");
;             const unsigned og = xb_add(&bar[XB_TOP], 1u);
;             const unsigned tg = og / nx;
;             if (og + 1u == (tg + 1u) * nx) xb_add(&bar[XB_TOPGEN], 1u);
;             else XB_SPIN(xb_ld(&bar[XB_TOPGEN]) == tg, bar);
;             __builtin_amdgcn_fence(__ATOMIC_ACQUIRE, "agent");
;             xb_add(&bar[XB_XGEN(b.x)], 1u);
;             asm volatile("s_waitcnt vmcnt(0)" ::: "memory");
.LBB0_879:
	s_or_b64 exec, exec, s[6:7]
	v_mov_b32_e32 v0, s29
	v_add_co_u32_e32 v0, vcc, 0x2000, v0
	v_mov_b32_e32 v1, s28
	s_nop 0
	v_addc_co_u32_e32 v1, vcc, 0, v1, vcc
	v_mov_b32_e32 v2, 1
	s_waitcnt vmcnt(0) lgkmcnt(0)
	buffer_inv sc1
	s_waitcnt vmcnt(0)
